# HGRN2 output phase: the 256 third-round items are spread one per workgroup (wave 0) instead of 8 per workgroup on 32 workgroups; RG-LRU next-item conv-input prefetch left in flight (halo mask deferred
# speedup vs baseline: 1.0470x; 1.0035x over previous
; __device__ __forceinline__ void hg_item(int it, int& tok0, int& h) { if (it < 1024) { const int b = it >> 9, n = (it >> 2) & 127; h = it & 3; tok0 = b * 8192 + n * 64; } else { const int s = it - 1024; h = s & 3; tok0 = TPROMPT + (s >> 2) * 64; } }
; __device__ __forceinline__ void hgrn_c_phase(KA A, int lane, int wave) {
;     ...
;     for (int wi = gw; wi < 4352; wi += NGW) {
;         const int it = wi >> 2, mt = wi & 3; int tok0, h; hg_item(it, tok0, h);
;         const int tok = tok0 + 16 * mt + fr;
;         f32x4 acc[8];
; #pragma unroll
;         for (int mi = 0; mi < 8; ++mi) acc[mi] = (f32x4){0.f, 0.f, 0.f, 0.f};
; #pragma unroll
;         for (int kk = 0; kk < 4; ++kk) {
;             const bf16x8 qb = *(const bf16x8*)(QT + (size_t)tok * 512 + h * 128 + 32 * kk + 8 * fq);
; #pragma unroll
;             for (int mi = 0; mi < 8; ++mi) { const bf16x8 sa = *(const bf16x8*)(SNT + (size_t)it * 16384 + (32 * (mi >> 1) + 8 * (fr >> 2) + 4 * (mi & 1) + (fr & 3)) * 128 + 32 * kk + 8 * fq);
;                 acc[mi] = __builtin_amdgcn_mfma_f32_16x16x32_bf16(sa, qb, acc[mi], 0, 0, 0); }
;         }
.LBB0_1121:
	s_ashr_i32 s6, s0, 2
	s_lshl_b32 s5, s6, 4
	v_and_or_b32 v2, s2, 48, v1
	s_ashr_i32 s7, s6, 31
	s_and_b32 s28, s5, 0xffffffc0
	s_lshl_b32 s20, s6, 7
	s_lshl_b64 s[6:7], s[6:7], 15
	v_or_b32_e32 v24, s28, v2
	v_lshl_add_u64 v[26:27], v[4:5], 0, s[6:7]
	v_ashrrev_i32_e32 v25, 31, v24
	s_and_b32 s5, s20, 0x180
	v_lshl_add_u64 v[72:73], v[26:27], 0, v[10:11]
	v_lshlrev_b64 v[124:125], 10, v[24:25]
	s_lshl_b32 s20, s5, 1
	v_lshl_add_u64 v[34:35], v[26:27], 0, v[8:9]
	v_lshl_add_u64 v[74:75], v[26:27], 0, v[12:13]
	v_lshl_add_u64 v[76:77], v[26:27], 0, v[14:15]
	v_lshl_add_u64 v[78:79], v[26:27], 0, v[16:17]
	v_lshl_add_u64 v[80:81], v[26:27], 0, v[18:19]
	v_lshl_add_u64 v[82:83], v[26:27], 0, v[20:21]
	v_lshl_add_u64 v[84:85], v[26:27], 0, 64
	v_lshl_add_u64 v[86:87], v[26:27], 0, s[22:23]
	v_lshl_add_u64 v[96:97], v[26:27], 0, s[24:25]
	global_load_dwordx4 v[26:29], v[72:73], off
	global_load_dwordx4 v[30:33], v[74:75], off
	global_load_dwordx4 v[40:43], v[76:77], off
	global_load_dwordx4 v[44:47], v[78:79], off
	global_load_dwordx4 v[48:51], v[80:81], off
	global_load_dwordx4 v[52:55], v[82:83], off
	global_load_dwordx4 v[56:59], v[34:35], off
	global_load_dwordx4 v[60:63], v[34:35], off offset:64
	global_load_dwordx4 v[64:67], v[34:35], off offset:1024
	global_load_dwordx4 v[68:71], v[34:35], off offset:1088
	v_lshl_add_u64 v[72:73], s[14:15], 0, v[124:125]
	v_lshl_add_u64 v[72:73], v[72:73], 0, s[20:21]
	v_lshl_add_u64 v[112:113], v[72:73], 0, v[6:7]
	global_load_dwordx4 v[72:75], v[112:113], off
	global_load_dwordx4 v[76:79], v[112:113], off offset:64
	v_or_b32_e32 v2, s5, v0
	v_lshlrev_b32_e32 v39, 2, v2
	v_lshl_add_u64 v[100:101], v[84:85], 0, v[10:11]
	v_lshl_add_u64 v[102:103], v[84:85], 0, v[12:13]
	v_lshl_add_u64 v[104:105], v[84:85], 0, v[14:15]
	v_lshl_add_u64 v[106:107], v[84:85], 0, v[16:17]
	v_lshl_add_u64 v[108:109], v[84:85], 0, v[18:19]
	v_lshl_add_u64 v[110:111], v[84:85], 0, v[20:21]
	global_load_dwordx4 v[80:83], v[34:35], off offset:128
	v_lshl_add_u64 v[114:115], v[86:87], 0, v[10:11]
	v_lshl_add_u64 v[116:117], v[86:87], 0, v[12:13]
	v_lshl_add_u64 v[118:119], v[86:87], 0, v[14:15]
	v_lshl_add_u64 v[120:121], v[86:87], 0, v[16:17]
	v_lshl_add_u64 v[122:123], v[86:87], 0, v[18:19]
	v_lshl_add_u64 v[126:127], v[86:87], 0, v[20:21]
	global_load_dwordx4 v[84:87], v[34:35], off offset:192
	global_load_dwordx4 v[88:91], v[34:35], off offset:1152
	global_load_dwordx4 v[92:95], v[34:35], off offset:1216
	v_lshl_add_u64 v[128:129], v[96:97], 0, v[10:11]
	v_lshl_add_u64 v[130:131], v[96:97], 0, v[12:13]
	v_lshl_add_u64 v[132:133], v[96:97], 0, v[14:15]
	v_lshl_add_u64 v[134:135], v[96:97], 0, v[16:17]
	v_lshl_add_u64 v[136:137], v[96:97], 0, v[18:19]
	v_lshl_add_u64 v[138:139], v[96:97], 0, v[20:21]
	v_lshlrev_b64 v[140:141], 11, v[24:25]
	s_lshl_b32 s20, s5, 2
	v_lshlrev_b32_e32 v2, 1, v2
	s_add_i32 s0, s0, s1
	s_add_i32 s2, s2, s3
	s_cmpk_lt_i32 s0, 0x1000
	s_cbranch_scc1 .Lhgc_ctl_done
	s_cmpk_lt_i32 s0, 0x1800
	s_cbranch_scc0 .Lhgc_ctl_done
	s_cmp_eq_u32 s72, 0
	s_cbranch_scc0 .Lhgc_ctl_done
	s_add_i32 s0, s96, 0x1000
	s_lshl_b32 s2, s0, 4
	s_cmp_eq_u32 s0, s0
.Lhgc_ctl_done:
	s_waitcnt vmcnt(0)
	v_mfma_f32_16x16x32_bf16 v[56:59], v[56:59], v[72:75], 0
	v_mfma_f32_16x16x32_bf16 v[64:67], v[64:67], v[72:75], 0
	v_mfma_f32_16x16x32_bf16 v[26:29], v[26:29], v[72:75], 0
	v_mfma_f32_16x16x32_bf16 v[30:33], v[30:33], v[72:75], 0
	v_mfma_f32_16x16x32_bf16 v[40:43], v[40:43], v[72:75], 0
	v_mfma_f32_16x16x32_bf16 v[44:47], v[44:47], v[72:75], 0
	v_mfma_f32_16x16x32_bf16 v[48:51], v[48:51], v[72:75], 0
	v_mfma_f32_16x16x32_bf16 v[52:55], v[52:55], v[72:75], 0
	global_load_dwordx4 v[72:75], v39, s[10:11] offset:16
	global_load_dwordx4 v[96:99], v39, s[10:11]
	v_mfma_f32_16x16x32_bf16 v[56:59], v[60:63], v[76:79], v[56:59]
	global_load_dwordx4 v[60:63], v[100:101], off
	v_mfma_f32_16x16x32_bf16 v[64:67], v[68:71], v[76:79], v[64:67]
	global_load_dwordx4 v[68:71], v[102:103], off
	s_waitcnt vmcnt(1)
	v_mfma_f32_16x16x32_bf16 v[24:27], v[60:63], v[76:79], v[26:29]
	global_load_dwordx4 v[60:63], v[104:105], off
	s_waitcnt vmcnt(1)
	v_mfma_f32_16x16x32_bf16 v[28:31], v[68:71], v[76:79], v[30:33]
	s_nop 2
	global_load_dwordx4 v[32:35], v[106:107], off
	s_waitcnt vmcnt(1)
	v_mfma_f32_16x16x32_bf16 v[40:43], v[60:63], v[76:79], v[40:43]
	global_load_dwordx4 v[60:63], v[108:109], off
	s_waitcnt vmcnt(1)
	v_mfma_f32_16x16x32_bf16 v[32:35], v[32:35], v[76:79], v[44:47]
	s_nop 2
	global_load_dwordx4 v[44:47], v[110:111], off
	global_load_dwordx4 v[68:71], v[114:115], off
	global_load_dwordx4 v[100:103], v[116:117], off
	s_waitcnt vmcnt(2)
	v_mfma_f32_16x16x32_bf16 v[44:47], v[44:47], v[76:79], v[52:55]
	v_mfma_f32_16x16x32_bf16 v[48:51], v[60:63], v[76:79], v[48:51]
	global_load_dwordx4 v[60:63], v[118:119], off
	global_load_dwordx4 v[104:107], v[120:121], off
	global_load_dwordx4 v[108:111], v[122:123], off
	global_load_dwordx4 v[52:55], v[112:113], off offset:128
	global_load_dwordx4 v[76:79], v[112:113], off offset:192
	s_nop 0
	global_load_dwordx4 v[112:115], v[130:131], off
	s_waitcnt vmcnt(2)
	v_mfma_f32_16x16x32_bf16 v[56:59], v[80:83], v[52:55], v[56:59]
	global_load_dwordx4 v[80:83], v[126:127], off
	v_mfma_f32_16x16x32_bf16 v[64:67], v[88:91], v[52:55], v[64:67]
	global_load_dwordx4 v[88:91], v[128:129], off
	v_mfma_f32_16x16x32_bf16 v[28:31], v[100:103], v[52:55], v[28:31]
	global_load_dwordx4 v[100:103], v[132:133], off
	v_mfma_f32_16x16x32_bf16 v[68:71], v[68:71], v[52:55], v[24:27]
	v_mfma_f32_16x16x32_bf16 v[40:43], v[60:63], v[52:55], v[40:43]
	global_load_dwordx4 v[60:63], v[134:135], off
	global_load_dwordx4 v[116:119], v[136:137], off
	global_load_dwordx4 v[120:123], v[138:139], off
	v_lshl_add_u64 v[26:27], s[18:19], 0, v[124:125]
	v_lshl_add_u64 v[26:27], v[26:27], 0, v[2:3]
	v_mfma_f32_16x16x32_bf16 v[32:35], v[104:107], v[52:55], v[32:35]
	v_lshl_add_u64 v[104:105], s[16:17], 0, v[140:141]
	v_lshl_add_u64 v[24:25], s[12:13], 0, v[140:141]
	v_lshl_add_u64 v[24:25], v[24:25], 0, s[26:27]
	v_mfma_f32_16x16x32_bf16 v[48:51], v[108:111], v[52:55], v[48:51]
	v_lshl_add_u64 v[124:125], v[24:25], 0, v[2:3]
	s_waitcnt vmcnt(5)
; __device__ __forceinline__ void hgrn_c_phase(KA A, int lane, int wave) {
;     ...
;         for (int kk = 0; kk < 4; ++kk) {
;             const bf16x8 qb = *(const bf16x8*)(QT + (size_t)tok * 512 + h * 128 + 32 * kk + 8 * fq);
; #pragma unroll
;             for (int mi = 0; mi < 8; ++mi) { const bf16x8 sa = *(const bf16x8*)(SNT + (size_t)it * 16384 + (32 * (mi >> 1) + 8 * (fr >> 2) + 4 * (mi & 1) + (fr & 3)) * 128 + 32 * kk + 8 * fq);
;                 acc[mi] = __builtin_amdgcn_mfma_f32_16x16x32_bf16(sa, qb, acc[mi], 0, 0, 0); }
;         }
;         float ss = 0.f;
; #pragma unroll
;         for (int mi = 0; mi < 8; ++mi) { acc[mi] = acc[mi] + *(const f32x4*)(OI + (size_t)tok * 512 + h * 128 + 32 * (mi >> 1) + 8 * fq + 4 * (mi & 1));
;             ss += (acc[mi].x * acc[mi].x + acc[mi].y * acc[mi].y) + (acc[mi].z * acc[mi].z + acc[mi].w * acc[mi].w); }
;         ss += __shfl_xor(ss, 16); ss += __shfl_xor(ss, 32);
	v_mfma_f32_16x16x32_bf16 v[44:47], v[80:83], v[52:55], v[44:47]
	v_lshl_add_u64 v[80:81], v[104:105], 0, s[20:21]
	v_lshl_add_u64 v[126:127], v[80:81], 0, v[22:23]
	global_load_dwordx4 v[52:55], v[26:27], off
	global_load_dwordx4 v[80:83], v[126:127], off
	v_mfma_f32_16x16x32_bf16 v[56:59], v[84:87], v[76:79], v[56:59]
	s_waitcnt vmcnt(1)
	v_lshlrev_b32_e32 v128, 16, v53
	v_mfma_f32_16x16x32_bf16 v[64:67], v[92:95], v[76:79], v[64:67]
	global_load_dwordx4 v[84:87], v[126:127], off offset:16
	global_load_dwordx4 v[92:95], v[126:127], off offset:128
	v_and_b32_e32 v129, 0xffff0000, v53
	v_lshlrev_b32_e32 v130, 16, v54
	v_mfma_f32_16x16x32_bf16 v[68:71], v[88:91], v[76:79], v[68:71]
	global_load_dwordx4 v[88:91], v[126:127], off offset:144
	global_load_dwordx4 v[104:107], v[126:127], off offset:256
	v_mfma_f32_16x16x32_bf16 v[28:31], v[112:115], v[76:79], v[28:31]
	global_load_dwordx4 v[108:111], v[126:127], off offset:272
	global_load_dwordx4 v[112:115], v[126:127], off offset:384
	v_mfma_f32_16x16x32_bf16 v[40:43], v[100:103], v[76:79], v[40:43]
	global_load_dwordx4 v[100:103], v[126:127], off offset:400
	v_lshlrev_b32_e32 v126, 16, v52
	v_and_b32_e32 v127, 0xffff0000, v52
	v_mfma_f32_16x16x32_bf16 v[44:47], v[120:123], v[76:79], v[44:47]
	s_waitcnt vmcnt(7)
	v_pk_add_f32 v[52:53], v[58:59], v[82:83]
	s_waitcnt vmcnt(6)
	v_pk_add_f32 v[58:59], v[64:65], v[84:85]
	v_mfma_f32_16x16x32_bf16 v[32:35], v[60:63], v[76:79], v[32:35]
	s_waitcnt vmcnt(5)
	v_pk_add_f32 v[60:61], v[70:71], v[94:95]
	v_pk_add_f32 v[62:63], v[68:69], v[92:93]
	s_waitcnt vmcnt(4)
	v_pk_add_f32 v[64:65], v[30:31], v[90:91]
	v_mfma_f32_16x16x32_bf16 v[48:51], v[116:119], v[76:79], v[48:51]
	v_and_b32_e32 v116, 0xffff0000, v54
	v_lshlrev_b32_e32 v117, 16, v55
	v_and_b32_e32 v118, 0xffff0000, v55
	v_pk_add_f32 v[54:55], v[56:57], v[80:81]
	v_pk_add_f32 v[56:57], v[66:67], v[86:87]
	s_waitcnt vmcnt(3)
	v_pk_add_f32 v[68:69], v[42:43], v[106:107]
	v_mov_b32_e32 v42, v55
	s_waitcnt vmcnt(0)
	v_pk_add_f32 v[30:31], v[46:47], v[102:103]
	v_mov_b32_e32 v43, v59
	v_mov_b32_e32 v46, v53
	v_mov_b32_e32 v47, v57
	v_pk_add_f32 v[66:67], v[28:29], v[88:89]
	v_pk_add_f32 v[70:71], v[40:41], v[104:105]
	v_pk_add_f32 v[76:77], v[34:35], v[110:111]
	v_pk_add_f32 v[78:79], v[32:33], v[108:109]
	v_pk_add_f32 v[28:29], v[50:51], v[114:115]
	v_pk_add_f32 v[32:33], v[48:49], v[112:113]
	v_pk_add_f32 v[34:35], v[44:45], v[100:101]
	v_mov_b32_e32 v40, v54
	v_mov_b32_e32 v41, v58
	v_mov_b32_e32 v44, v52
	v_mov_b32_e32 v45, v56
	v_pk_mul_f32 v[48:49], v[60:61], v[60:61]
	v_pk_mul_f32 v[50:51], v[62:63], v[62:63]
	v_pk_mul_f32 v[42:43], v[42:43], v[42:43]
	v_pk_mul_f32 v[46:47], v[46:47], v[46:47]
	v_pk_mov_b32 v[92:93], v[50:51], v[48:49] op_sel:[1,0]
	v_mov_b32_e32 v51, v49
	v_pk_fma_f32 v[40:41], v[40:41], v[40:41], v[42:43]
	v_pk_fma_f32 v[42:43], v[44:45], v[44:45], v[46:47]
	v_mul_f32_e32 v80, v67, v67
	v_mul_f32_e32 v82, v65, v65
	v_pk_add_f32 v[44:45], v[92:93], v[50:51]
	v_pk_add_f32 v[40:41], v[40:41], v[42:43]
	v_mul_f32_e32 v91, v70, v70
	v_mul_f32_e32 v94, v71, v71
	v_mul_f32_e32 v95, v68, v68
	v_mul_f32_e32 v100, v69, v69
	v_pk_fma_f32 v[48:49], v[66:67], v[66:67], v[80:81] op_sel_hi:[1,1,0]
	v_pk_fma_f32 v[80:81], v[64:65], v[64:65], v[82:83] op_sel_hi:[1,1,0]
	v_pk_add_f32 v[42:43], v[44:45], v[44:45] op_sel:[0,1] op_sel_hi:[1,0]
	v_pk_add_f32 v[40:41], v[40:41], v[40:41] op_sel:[0,1] op_sel_hi:[1,0]
	v_pk_mul_f32 v[84:85], v[76:77], v[76:77]
	v_pk_mul_f32 v[86:87], v[78:79], v[78:79]
	v_mov_b32_e32 v49, v95
	v_mov_b32_e32 v81, v100
	v_mov_b32_e32 v43, v94
	v_mov_b32_e32 v41, v91
	v_pk_mov_b32 v[82:83], v[86:87], v[84:85] op_sel:[1,0]
	v_mov_b32_e32 v87, v85
	v_pk_add_f32 v[44:45], v[48:49], v[80:81]
	v_pk_add_f32 v[40:41], v[40:41], v[42:43]
	v_mul_f32_e32 v88, v33, v33
	v_mul_f32_e32 v90, v29, v29
	v_pk_add_f32 v[46:47], v[82:83], v[86:87]
	v_pk_add_f32 v[40:41], v[40:41], v[44:45]
	v_mul_f32_e32 v101, v34, v34
	v_mul_f32_e32 v102, v35, v35
	v_mul_f32_e32 v103, v30, v30
	v_mul_f32_e32 v104, v31, v31
	v_pk_fma_f32 v[84:85], v[32:33], v[32:33], v[88:89] op_sel_hi:[1,1,0]
	v_pk_fma_f32 v[88:89], v[28:29], v[28:29], v[90:91] op_sel_hi:[1,1,0]
	v_pk_add_f32 v[46:47], v[46:47], v[46:47] op_sel:[0,1] op_sel_hi:[1,0]
	v_pk_add_f32 v[40:41], v[40:41], v[40:41] op_sel:[0,1] op_sel_hi:[1,0]
	v_mov_b32_e32 v85, v103
	v_mov_b32_e32 v89, v104
	v_mov_b32_e32 v47, v102
	v_mov_b32_e32 v41, v101
	v_pk_add_f32 v[48:49], v[84:85], v[88:89]
	v_pk_add_f32 v[40:41], v[40:41], v[46:47]
	s_nop 0
	v_pk_add_f32 v[40:41], v[40:41], v[48:49]
	s_nop 0
	v_add_f32_e32 v40, v40, v41
	ds_bpermute_b32 v41, v36, v40
	s_waitcnt lgkmcnt(0)
	v_add_f32_e32 v40, v40, v41
	ds_bpermute_b32 v41, v37, v40
	s_waitcnt lgkmcnt(0)
; __device__ __forceinline__ unsigned pk2(float lo, float hi) { return pg8::cvt_pk_bf16(lo, hi); }
; __device__ __forceinline__ float bflo(unsigned w) { return __uint_as_float(w << 16); }
; __device__ __forceinline__ float bfhi(unsigned w) { return __uint_as_float(w & 0xffff0000u); }
; __device__ __forceinline__ void hgrn_c_phase(KA A, int lane, int wave) {
;     ...
;         const float rstd = rsqrtf(ss * (1.f / 128.f) + EPSV);
; #pragma unroll
;         for (int mp = 0; mp < 4; ++mp) { const int vcol = h * 128 + 32 * mp + 8 * fq;
;             const f32x4 g0 = *(const f32x4*)(gn + vcol), g1 = *(const f32x4*)(gn + vcol + 4); const u32x4 gw4 = *(const u32x4*)(GB + (size_t)tok * 512 + vcol);
;             const f32x4 y0 = acc[2 * mp] * rstd * g0, y1 = acc[2 * mp + 1] * rstd * g1;
;             u32x4 w; w.x = pk2(y0.x * bflo(gw4.x), y0.y * bfhi(gw4.x)); w.y = pk2(y0.z * bflo(gw4.y), y0.w * bfhi(gw4.y));
;             w.z = pk2(y1.x * bflo(gw4.z), y1.y * bfhi(gw4.z)); w.w = pk2(y1.z * bflo(gw4.w), y1.w * bfhi(gw4.w));
;             *(u32x4*)(OC + (size_t)tok * DM + 512 + vcol) = w; }
;     }
	v_add_f32_e32 v40, v40, v41
	v_fmamk_f32 v40, v40, 0x3c000000, v38
	v_mul_f32_e32 v41, 0x4b800000, v40
	v_cmp_gt_f32_e32 vcc, s4, v40
	s_nop 1
	v_cndmask_b32_e32 v40, v40, v41, vcc
	v_rsq_f32_e32 v40, v40
	s_nop 0
	v_mul_f32_e32 v41, 0x45800000, v40
	v_cndmask_b32_e32 v80, v40, v41, vcc
	v_pk_mul_f32 v[40:41], v[54:55], v[80:81] op_sel_hi:[1,0]
	v_pk_mul_f32 v[42:43], v[52:53], v[80:81] op_sel_hi:[1,0]
	v_pk_mul_f32 v[44:45], v[58:59], v[80:81] op_sel_hi:[1,0]
	v_pk_mul_f32 v[46:47], v[56:57], v[80:81] op_sel_hi:[1,0]
	v_pk_mul_f32 v[42:43], v[98:99], v[42:43]
	v_pk_mul_f32 v[40:41], v[96:97], v[40:41]
	v_pk_mul_f32 v[46:47], v[74:75], v[46:47]
	v_pk_mul_f32 v[44:45], v[72:73], v[44:45]
	v_mul_f32_e32 v40, v40, v126
	v_mul_f32_e32 v41, v41, v127
	v_mul_f32_e32 v42, v42, v128
	v_mul_f32_e32 v43, v43, v129
	v_mul_f32_e32 v44, v44, v130
	v_mul_f32_e32 v45, v45, v116
	v_mul_f32_e32 v46, v46, v117
	v_mul_f32_e32 v47, v47, v118
	v_cvt_pk_bf16_f32 v40, v40, v41
	v_cvt_pk_bf16_f32 v41, v42, v43
	v_cvt_pk_bf16_f32 v42, v44, v45
	v_cvt_pk_bf16_f32 v43, v46, v47
	global_store_dwordx4 v[124:125], v[40:43], off
	global_load_dwordx4 v[44:47], v[26:27], off offset:64
	s_nop 0
	global_load_dwordx4 v[40:43], v39, s[10:11] offset:128
	global_load_dwordx4 v[48:51], v39, s[10:11] offset:144
	v_pk_mul_f32 v[54:55], v[62:63], v[80:81] op_sel_hi:[1,0]
	v_pk_mul_f32 v[56:57], v[60:61], v[80:81] op_sel_hi:[1,0]
	v_pk_mul_f32 v[58:59], v[66:67], v[80:81] op_sel_hi:[1,0]
	v_pk_mul_f32 v[60:61], v[64:65], v[80:81] op_sel_hi:[1,0]
	v_mov_b32_e32 v53, v3
	v_or_b32_e32 v52, 64, v2
	v_lshl_add_u64 v[52:53], v[24:25], 0, v[52:53]
	v_pk_mul_f32 v[30:31], v[30:31], v[80:81] op_sel_hi:[1,0]
	s_waitcnt vmcnt(2)
	v_lshlrev_b32_e32 v62, 16, v44
	v_and_b32_e32 v63, 0xffff0000, v44
	v_lshlrev_b32_e32 v64, 16, v45
	v_and_b32_e32 v65, 0xffff0000, v45
	v_lshlrev_b32_e32 v66, 16, v46
	v_and_b32_e32 v67, 0xffff0000, v46
	v_lshlrev_b32_e32 v72, 16, v47
	v_and_b32_e32 v73, 0xffff0000, v47
	s_waitcnt vmcnt(1)
	v_pk_mul_f32 v[42:43], v[42:43], v[56:57]
	v_pk_mul_f32 v[40:41], v[40:41], v[54:55]
	s_waitcnt vmcnt(0)
	v_pk_mul_f32 v[44:45], v[50:51], v[60:61]
	v_pk_mul_f32 v[46:47], v[48:49], v[58:59]
	v_mul_f32_e32 v40, v40, v62
	v_mul_f32_e32 v41, v41, v63
	v_mul_f32_e32 v42, v42, v64
	v_mul_f32_e32 v43, v43, v65
	v_mul_f32_e32 v46, v46, v66
	v_mul_f32_e32 v47, v47, v67
	v_mul_f32_e32 v44, v44, v72
	v_mul_f32_e32 v45, v45, v73
	v_cvt_pk_bf16_f32 v40, v40, v41
	v_cvt_pk_bf16_f32 v41, v42, v43
	v_cvt_pk_bf16_f32 v42, v46, v47
	v_cvt_pk_bf16_f32 v43, v44, v45
	global_load_dwordx4 v[44:47], v[26:27], off offset:128
	v_pk_mul_f32 v[54:55], v[70:71], v[80:81] op_sel_hi:[1,0]
	global_store_dwordx4 v[52:53], v[40:43], off
	global_load_dwordx4 v[40:43], v39, s[10:11] offset:256
	s_nop 0
	global_load_dwordx4 v[48:51], v39, s[10:11] offset:272
	v_pk_mul_f32 v[56:57], v[68:69], v[80:81] op_sel_hi:[1,0]
	v_mov_b32_e32 v53, v3
	v_or_b32_e32 v52, 0x80, v2
	v_pk_mul_f32 v[58:59], v[78:79], v[80:81] op_sel_hi:[1,0]
	v_pk_mul_f32 v[60:61], v[76:77], v[80:81] op_sel_hi:[1,0]
	v_lshl_add_u64 v[52:53], v[24:25], 0, v[52:53]
	v_or_b32_e32 v2, 0xc0, v2
	s_waitcnt vmcnt(3)
	v_lshlrev_b32_e32 v62, 16, v44
	v_and_b32_e32 v63, 0xffff0000, v44
	v_lshlrev_b32_e32 v64, 16, v45
	v_and_b32_e32 v65, 0xffff0000, v45
	s_waitcnt vmcnt(1)
	v_pk_mul_f32 v[42:43], v[56:57], v[42:43]
	v_pk_mul_f32 v[40:41], v[54:55], v[40:41]
	v_lshlrev_b32_e32 v66, 16, v46
	v_and_b32_e32 v67, 0xffff0000, v46
	v_lshlrev_b32_e32 v68, 16, v47
	v_and_b32_e32 v69, 0xffff0000, v47
	s_waitcnt vmcnt(0)
	v_pk_mul_f32 v[44:45], v[60:61], v[50:51]
	v_pk_mul_f32 v[46:47], v[58:59], v[48:49]
	v_mul_f32_e32 v40, v40, v62
	v_mul_f32_e32 v41, v41, v63
	v_mul_f32_e32 v42, v42, v64
	v_mul_f32_e32 v43, v43, v65
	v_mul_f32_e32 v46, v46, v66
	v_mul_f32_e32 v47, v47, v67
	v_mul_f32_e32 v44, v44, v68
	v_mul_f32_e32 v45, v45, v69
	v_cvt_pk_bf16_f32 v40, v40, v41
	v_cvt_pk_bf16_f32 v41, v42, v43
	v_cvt_pk_bf16_f32 v42, v46, v47
	v_cvt_pk_bf16_f32 v43, v44, v45
	global_store_dwordx4 v[52:53], v[40:43], off
	global_load_dwordx4 v[44:47], v[26:27], off offset:192
	s_nop 0
	global_load_dwordx4 v[40:43], v39, s[10:11] offset:384
	global_load_dwordx4 v[48:51], v39, s[10:11] offset:400
	v_lshl_add_u64 v[52:53], v[24:25], 0, v[2:3]
	v_pk_mul_f32 v[24:25], v[32:33], v[80:81] op_sel_hi:[1,0]
	v_pk_mul_f32 v[26:27], v[28:29], v[80:81] op_sel_hi:[1,0]
	v_pk_mul_f32 v[28:29], v[34:35], v[80:81] op_sel_hi:[1,0]
	s_waitcnt vmcnt(2)
	v_lshlrev_b32_e32 v2, 16, v44
	v_and_b32_e32 v32, 0xffff0000, v44
	v_lshlrev_b32_e32 v33, 16, v45
	v_and_b32_e32 v34, 0xffff0000, v45
	v_lshlrev_b32_e32 v35, 16, v46
	s_waitcnt vmcnt(1)
	v_pk_mul_f32 v[26:27], v[26:27], v[42:43]
	v_pk_mul_f32 v[24:25], v[24:25], v[40:41]
	s_waitcnt vmcnt(0)
	v_pk_mul_f32 v[28:29], v[28:29], v[48:49]
	v_and_b32_e32 v39, 0xffff0000, v46
	v_lshlrev_b32_e32 v44, 16, v47
	v_and_b32_e32 v45, 0xffff0000, v47
	v_pk_mul_f32 v[30:31], v[30:31], v[50:51]
	v_mul_f32_e32 v2, v24, v2
	v_mul_f32_e32 v24, v25, v32
	v_mul_f32_e32 v25, v26, v33
	v_mul_f32_e32 v26, v27, v34
	v_mul_f32_e32 v27, v28, v35
	v_mul_f32_e32 v28, v29, v39
	v_mul_f32_e32 v29, v30, v44
	v_mul_f32_e32 v30, v31, v45
	v_cvt_pk_bf16_f32 v24, v2, v24
	v_cvt_pk_bf16_f32 v25, v25, v26
	v_cvt_pk_bf16_f32 v26, v27, v28
	v_cvt_pk_bf16_f32 v27, v29, v30
	global_store_dwordx4 v[52:53], v[24:27], off
	s_cbranch_scc1 .LBB0_1121

; template <bool UNUSED_>
; __device__ __forceinline__ void lru_phase(KA A, LAS unsigned char* lds, int tid, int lane, int wave) {
;     ...
;         if (li + (int)gridDim.x < 2176) LRU_PREFETCH(li + (int)gridDim.x);
.LBB0_1715:
	s_load_dword s88, s[34:35], 0x0
	s_mov_b64 s[98:99], 0
	v_mov_b32_e32 v70, v164
	v_mov_b32_e32 v71, v163
	v_mov_b32_e32 v152, v162
	v_mov_b32_e32 v153, v161
	s_waitcnt lgkmcnt(0)
	s_add_i32 s88, s88, s59
	s_cmpk_gt_i32 s88, 0x87f
	s_cselect_b64 s[60:61], -1, 0
	s_and_b64 vcc, exec, s[60:61]
	v_mov_b32_e32 v154, v165
	v_mov_b32_e32 v155, v166
	v_mov_b32_e32 v156, v169
	v_mov_b32_e32 v157, v171
	v_mov_b32_e32 v54, v167
	v_mov_b32_e32 v72, v170
	v_mov_b32_e32 v73, v172
	v_mov_b32_e32 v74, v173
	v_mov_b32_e32 v75, v174
	v_mov_b32_e32 v149, v175
	v_mov_b32_e32 v150, v176
	v_mov_b32_e32 v151, v177
	v_mov_b32_e32 v158, v178
	v_mov_b32_e32 v159, v179
	v_mov_b32_e32 v160, v180
	s_cbranch_vccnz .LBB0_1729
	s_ashr_i32 s0, s88, 3
	s_add_i32 s2, s0, 0xffffff00
	s_lshl_b32 s1, s88, 3
	s_and_b32 s33, s1, 0xffffe000
	s_lshl_b32 s1, s2, 6
	s_add_i32 s66, s1, 0x4000
	s_lshl_b32 s1, s0, 6
	s_and_b32 s67, s1, 0x1fc0
	s_cmpk_lt_i32 s0, 0x100
	s_cselect_b64 s[10:11], -1, 0
	s_and_b64 s[0:1], s[10:11], exec
	s_cselect_b32 s0, s33, s66
	s_cselect_b32 s1, s67, 0
	s_lshl_b32 s33, s88, 7
	s_and_b32 s33, s33, 0x380
	s_add_i32 s1, s1, s3
	v_or_b32_e32 v54, s33, v53
	s_cmp_eq_u32 s1, 0
	v_lshlrev_b32_e32 v54, 2, v54
	s_cselect_b64 s[66:67], -1, 0
	s_cmp_lg_u32 s1, 0
	v_lshl_add_u64 v[70:71], s[30:31], 0, v[54:55]
	s_cselect_b64 s[68:69], -1, 0
	s_mov_b64 s[72:73], -1
	s_and_b64 vcc, exec, s[66:67]
	s_cbranch_vccnz .LBB0_1718
	s_add_i32 s33, s0, s1
	s_add_i32 s70, s33, -3
	s_ashr_i32 s71, s70, 31
	s_lshl_b64 s[70:71], s[70:71], 12
	v_lshl_add_u64 v[74:75], v[70:71], 0, s[70:71]
	s_mov_b64 s[72:73], 0

.LBB0_1728:
	s_ashr_i32 s69, s68, 31
	s_lshl_b64 s[0:1], s[68:69], 12
	v_lshl_add_u64 v[72:73], v[70:71], 0, s[0:1]
	s_or_b32 s0, s68, 1
	s_ashr_i32 s1, s0, 31
	s_lshl_b64 s[0:1], s[0:1], 12
	global_load_dword v210, v[74:75], off
	v_lshl_add_u64 v[74:75], v[70:71], 0, s[0:1]
	s_or_b32 s0, s68, 2
	s_ashr_i32 s1, s0, 31
	s_lshl_b64 s[0:1], s[0:1], 12
	v_lshl_add_u64 v[152:153], v[70:71], 0, s[0:1]
	s_or_b32 s0, s68, 3
	s_ashr_i32 s1, s0, 31
	s_lshl_b64 s[0:1], s[0:1], 12
	v_lshl_add_u64 v[154:155], v[70:71], 0, s[0:1]
	s_or_b32 s0, s68, 4
	s_ashr_i32 s1, s0, 31
	s_lshl_b64 s[0:1], s[0:1], 12
	v_lshl_add_u64 v[156:157], v[70:71], 0, s[0:1]
	s_or_b32 s0, s68, 5
	s_ashr_i32 s1, s0, 31
	s_lshl_b64 s[0:1], s[0:1], 12
	v_lshl_add_u64 v[186:187], v[70:71], 0, s[0:1]
	s_or_b32 s0, s68, 6
	s_ashr_i32 s1, s0, 31
	s_lshl_b64 s[0:1], s[0:1], 12
	v_lshl_add_u64 v[188:189], v[70:71], 0, s[0:1]
	s_or_b32 s0, s68, 7
	s_ashr_i32 s1, s0, 31
	s_lshl_b64 s[0:1], s[0:1], 12
	v_lshl_add_u64 v[190:191], v[70:71], 0, s[0:1]
	s_or_b32 s0, s68, 8
	s_ashr_i32 s1, s0, 31
	s_lshl_b64 s[0:1], s[0:1], 12
	global_load_dword v151, v[72:73], off
	global_load_dword v150, v[74:75], off
	global_load_dword v149, v[152:153], off
	s_nop 0
	global_load_dword v75, v[154:155], off
	global_load_dword v74, v[156:157], off
	global_load_dword v73, v[186:187], off
	global_load_dword v72, v[188:189], off
	global_load_dword v54, v[190:191], off
	v_lshl_add_u64 v[152:153], v[70:71], 0, s[0:1]
	s_or_b32 s0, s68, 9
	s_ashr_i32 s1, s0, 31
	s_lshl_b64 s[0:1], s[0:1], 12
	v_lshl_add_u64 v[154:155], v[70:71], 0, s[0:1]
	s_or_b32 s0, s68, 10
	s_ashr_i32 s1, s0, 31
	s_lshl_b64 s[0:1], s[0:1], 12
	v_lshl_add_u64 v[186:187], v[70:71], 0, s[0:1]
	s_or_b32 s0, s68, 11
	s_ashr_i32 s1, s0, 31
	s_lshl_b64 s[0:1], s[0:1], 12
	v_lshl_add_u64 v[188:189], v[70:71], 0, s[0:1]
	s_or_b32 s0, s68, 12
	s_ashr_i32 s1, s0, 31
	s_lshl_b64 s[0:1], s[0:1], 12
	v_lshl_add_u64 v[190:191], v[70:71], 0, s[0:1]
	s_or_b32 s0, s68, 13
	s_ashr_i32 s1, s0, 31
	s_lshl_b64 s[0:1], s[0:1], 12
	v_lshl_add_u64 v[192:193], v[70:71], 0, s[0:1]
	s_or_b32 s0, s68, 14
	s_ashr_i32 s1, s0, 31
	s_lshl_b64 s[0:1], s[0:1], 12
	v_lshl_add_u64 v[194:195], v[70:71], 0, s[0:1]
	s_or_b32 s0, s68, 15
	s_ashr_i32 s1, s0, 31
	s_lshl_b64 s[0:1], s[0:1], 12
	v_lshl_add_u64 v[196:197], v[70:71], 0, s[0:1]
	global_load_dword v157, v[152:153], off
	global_load_dword v156, v[154:155], off
	s_nop 0
	global_load_dword v155, v[186:187], off
	global_load_dword v154, v[188:189], off
	global_load_dword v153, v[190:191], off
	global_load_dword v152, v[192:193], off
	global_load_dword v71, v[194:195], off
	global_load_dword v70, v[196:197], off
	s_and_b64 s[98:99], s[10:11], s[66:67]
	s_waitcnt vmcnt(19)
	s_branch .Llru_pf_done

; #define LBAR() do { asm volatile("s_waitcnt lgkmcnt(0)" ::: "memory"); __builtin_amdgcn_s_barrier(); asm volatile("" ::: "memory"); } while (0)
; __device__ __forceinline__ unsigned pk2(float lo, float hi) { return pg8::cvt_pk_bf16(lo, hi); }
; template <bool UNUSED_>
; __device__ __forceinline__ void lru_phase(KA A, LAS unsigned char* lds, int tid, int lane, int wave) {
;     ...
;         float xv[16], xm3 = xh[0], xm2 = xh[1], xm1 = xh[2];
; #pragma unroll
;         for (int i = 0; i < 16; ++i) xv[i] = xn[i];
;         if (li + (int)gridDim.x < 2176) LRU_PREFETCH(li + (int)gridDim.x);
;         asm volatile("" ::: "memory");
;         LBAR();
; #pragma unroll
;         for (int i = 0; i < 16; ++i) { const int t = 16 * tq + i; const float x0 = xv[i];
;             const float xc = cb + cw0 * xm3 + cw1 * xm2 + cw2 * xm1 + cw3 * x0;
;             XCf[t * LP + c] = xc; XCb[t * 136 + c] = (bf16_t)(pk2(xc, 0.f) & 0xffffu);
;             xm3 = xm2; xm2 = xm1; xm1 = x0; }
.Llru_pf_done:
	v_fma_f32 v180, v180, v184, v183
	v_fmac_f32_e32 v180, v179, v181
	v_fma_f32 v179, v179, v184, v183
	v_fmac_f32_e32 v180, v178, v69
	v_fmac_f32_e32 v179, v178, v181
	v_fma_f32 v178, v178, v184, v183
	v_fmac_f32_e32 v180, v177, v182
	v_fmac_f32_e32 v179, v177, v69
	v_fmac_f32_e32 v178, v177, v181
	v_fma_f32 v177, v177, v184, v183
	v_fmac_f32_e32 v179, v176, v182
	v_fmac_f32_e32 v178, v176, v69
	v_fmac_f32_e32 v177, v176, v181
	v_fma_f32 v176, v176, v184, v183
	v_fmac_f32_e32 v178, v175, v182
	v_fmac_f32_e32 v177, v175, v69
	v_fmac_f32_e32 v176, v175, v181
	v_fma_f32 v175, v175, v184, v183
	v_fmac_f32_e32 v177, v174, v182
	v_fmac_f32_e32 v176, v174, v69
	v_fmac_f32_e32 v175, v174, v181
	v_fma_f32 v174, v174, v184, v183
	v_fmac_f32_e32 v176, v173, v182
	v_fmac_f32_e32 v175, v173, v69
	v_fmac_f32_e32 v174, v173, v181
	v_fma_f32 v173, v173, v184, v183
	v_fmac_f32_e32 v175, v172, v182
	v_fmac_f32_e32 v174, v172, v69
	v_fmac_f32_e32 v173, v172, v181
	v_fma_f32 v172, v172, v184, v183
	v_fmac_f32_e32 v174, v170, v182
	v_fmac_f32_e32 v173, v170, v69
	v_fmac_f32_e32 v172, v170, v181
	v_fma_f32 v170, v170, v184, v183
	v_fmac_f32_e32 v173, v167, v182
	v_fmac_f32_e32 v172, v167, v69
	v_fmac_f32_e32 v170, v167, v181
	v_fma_f32 v167, v167, v184, v183
	v_add_u32_e32 v185, s4, v78
	v_fmac_f32_e32 v167, v171, v181
	s_waitcnt lgkmcnt(0)
	s_barrier
	ds_write_b32 v185, v180 offset:17408
	v_cvt_pk_bf16_f32 v180, v180, v55
	v_add_u32_e32 v185, s5, v79
	v_fmac_f32_e32 v170, v171, v69
	v_fmac_f32_e32 v167, v169, v69
	ds_write_b16 v185, v180
	v_add_u32_e32 v180, s6, v78
	v_add_u32_e32 v185, s7, v79
	v_fmac_f32_e32 v172, v171, v182
	v_fmac_f32_e32 v170, v169, v182
	v_fmac_f32_e32 v167, v166, v182
	ds_write_b32 v180, v179 offset:17408
	v_cvt_pk_bf16_f32 v179, v179, v55
	ds_write_b16 v185, v179
	ds_write_b32 v180, v178 offset:17924
	v_cvt_pk_bf16_f32 v178, v178, v55
	ds_write_b16 v185, v178 offset:272
	ds_write_b32 v180, v177 offset:18440
	v_cvt_pk_bf16_f32 v177, v177, v55
	ds_write_b16 v185, v177 offset:544
	ds_write_b32 v180, v176 offset:18956
	v_cvt_pk_bf16_f32 v176, v176, v55
	ds_write_b16 v185, v176 offset:816
	ds_write_b32 v180, v175 offset:19472
	v_cvt_pk_bf16_f32 v175, v175, v55
	ds_write_b16 v185, v175 offset:1088
	ds_write_b32 v180, v174 offset:19988
	v_cvt_pk_bf16_f32 v174, v174, v55
	ds_write_b16 v185, v174 offset:1360
	ds_write_b32 v180, v173 offset:20504
	v_cvt_pk_bf16_f32 v173, v173, v55
	ds_write_b16 v185, v173 offset:1632
	ds_write_b32 v180, v172 offset:21020
	v_cvt_pk_bf16_f32 v172, v172, v55
	ds_write_b16 v185, v172 offset:1904
	ds_write_b32 v180, v170 offset:21536
	v_cvt_pk_bf16_f32 v170, v170, v55
	ds_write_b16 v185, v170 offset:2176
	ds_write_b32 v180, v167 offset:22052
	v_cvt_pk_bf16_f32 v167, v167, v55
	ds_write_b16 v185, v167 offset:2448
	v_fma_f32 v167, v171, v184, v183
	v_fmac_f32_e32 v167, v169, v181
	v_fmac_f32_e32 v167, v166, v69
	v_fmac_f32_e32 v167, v165, v182
	ds_write_b32 v180, v167 offset:22568
	v_cvt_pk_bf16_f32 v167, v167, v55
	ds_write_b16 v185, v167 offset:2720
	v_fma_f32 v167, v169, v184, v183
	v_fmac_f32_e32 v167, v166, v181
	v_fma_f32 v166, v166, v184, v183
	v_fmac_f32_e32 v167, v165, v69
	v_fmac_f32_e32 v166, v165, v181
	v_fma_f32 v165, v165, v184, v183
	v_fmac_f32_e32 v183, v161, v184
	v_fmac_f32_e32 v165, v161, v181
	v_fmac_f32_e32 v183, v162, v181
	v_fmac_f32_e32 v166, v161, v69
	v_fmac_f32_e32 v165, v162, v69
	v_fmac_f32_e32 v183, v163, v69
	v_fmac_f32_e32 v167, v161, v182
	v_fmac_f32_e32 v166, v162, v182
	v_fmac_f32_e32 v165, v163, v182
	v_fmac_f32_e32 v183, v164, v182
	ds_write_b32 v180, v167 offset:23084
	v_cvt_pk_bf16_f32 v167, v167, v55
	ds_write_b16 v185, v167 offset:2992
	ds_write_b32 v180, v166 offset:23600
	v_cvt_pk_bf16_f32 v166, v166, v55
	ds_write_b16 v185, v166 offset:3264
	ds_write_b32 v180, v165 offset:24116
	v_cvt_pk_bf16_f32 v165, v165, v55
	ds_write_b16 v185, v165 offset:3536
	ds_write_b32 v180, v183 offset:24632
	v_cvt_pk_bf16_f32 v69, v183, v55
	ds_write_b16 v185, v69 offset:3808
	s_waitcnt lgkmcnt(0)
	s_barrier
; #define LAS __attribute__((address_space(3)))
; template <bool UNUSED_>
; __device__ __forceinline__ void lru_phase(KA A, LAS unsigned char* lds, int tid, int lane, int wave) {
;     ...
;             f32x4 accA[4], accX[4];
; #pragma unroll
;             for (int ni = 0; ni < 4; ++ni) { accA[ni] = (f32x4){0.f, 0.f, 0.f, 0.f}; accX[ni] = (f32x4){0.f, 0.f, 0.f, 0.f}; }
; #pragma unroll
;             for (int kk = 0; kk < 4; ++kk) {
; #pragma unroll
;                 for (int ni = 0; ni < 4; ++ni) { const bf16x8 xb = *(const LAS bf16x8*)(XCb + (16 * ni + fr) * 136 + 32 * kk + 8 * fq);
;                     accA[ni] = __builtin_amdgcn_mfma_f32_16x16x32_bf16(wa[kk], xb, accA[ni], 0, 0, 0);
;                     accX[ni] = __builtin_amdgcn_mfma_f32_16x16x32_bf16(wx[kk], xb, accX[ni], 0, 0, 0); }
;             }
;             float L8[4];
; #pragma unroll
;             for (int j = 0; j < 4; ++j) { const float e = __expf(-lam4[j]); L8[j] = -8.f * (e < 0.01f ? e * (1.f - e * (0.5f - e * 0.33333334f)) : __logf(1.f + e)); }
	ds_read_b128 v[162:165], v144
	ds_read_b128 v[170:173], v144 offset:64
	ds_read_b128 v[178:181], v144 offset:4352
	ds_read_b128 v[182:185], v144 offset:4416
	ds_read_b128 v[190:193], v144 offset:8704
	ds_read_b128 v[194:197], v144 offset:8768
	ds_read_b128 v[202:205], v145
	ds_read_b128 v[206:209], v145 offset:64
	s_waitcnt lgkmcnt(7)
	v_mfma_f32_16x16x32_bf16 v[174:177], v[44:47], v[162:165], 0
	v_mul_f32_e32 v32, 0xbfb8aa3b, v32
	v_exp_f32_e32 v69, v32
	v_mfma_f32_16x16x32_bf16 v[162:165], v[48:51], v[162:165], 0
	v_cmp_ngt_f32_e32 vcc, s82, v69
	s_waitcnt lgkmcnt(5)
	v_mfma_f32_16x16x32_bf16 v[186:189], v[44:47], v[178:181], 0
	v_mfma_f32_16x16x32_bf16 v[178:181], v[48:51], v[178:181], 0
	s_waitcnt lgkmcnt(3)
	v_mfma_f32_16x16x32_bf16 v[198:201], v[44:47], v[190:193], 0
	v_mfma_f32_16x16x32_bf16 v[190:193], v[48:51], v[190:193], 0
	s_waitcnt lgkmcnt(1)
	v_mfma_f32_16x16x32_bf16 v[44:47], v[44:47], v[202:205], 0
	v_mfma_f32_16x16x32_bf16 v[48:51], v[48:51], v[202:205], 0
	v_mfma_f32_16x16x32_bf16 v[174:177], v[36:39], v[170:173], v[174:177]
	v_mfma_f32_16x16x32_bf16 v[162:165], v[40:43], v[170:173], v[162:165]
	v_mfma_f32_16x16x32_bf16 v[170:173], v[36:39], v[182:185], v[186:189]
	v_mfma_f32_16x16x32_bf16 v[178:181], v[40:43], v[182:185], v[178:181]
	v_mfma_f32_16x16x32_bf16 v[182:185], v[36:39], v[194:197], v[198:201]
	v_mfma_f32_16x16x32_bf16 v[186:189], v[40:43], v[194:197], v[190:193]
	s_waitcnt lgkmcnt(0)
	v_mfma_f32_16x16x32_bf16 v[36:39], v[36:39], v[206:209], v[44:47]
	s_nop 2
	ds_read_b128 v[44:47], v144 offset:128
	ds_read_b128 v[190:193], v144 offset:192
	v_mfma_f32_16x16x32_bf16 v[40:43], v[40:43], v[206:209], v[48:51]
	s_waitcnt lgkmcnt(1)
	v_mfma_f32_16x16x32_bf16 v[48:51], v[24:27], v[44:47], v[174:177]
	v_mfma_f32_16x16x32_bf16 v[44:47], v[28:31], v[44:47], v[162:165]
	s_nop 2
	ds_read_b128 v[162:165], v144 offset:4480
	ds_read_b128 v[174:177], v144 offset:4544
	s_waitcnt lgkmcnt(1)
	v_mfma_f32_16x16x32_bf16 v[170:173], v[24:27], v[162:165], v[170:173]
	v_mfma_f32_16x16x32_bf16 v[162:165], v[28:31], v[162:165], v[178:181]
	s_nop 2
	ds_read_b128 v[178:181], v144 offset:8832
	ds_read_b128 v[194:197], v144 offset:8896
	s_waitcnt lgkmcnt(1)
	v_mfma_f32_16x16x32_bf16 v[182:185], v[24:27], v[178:181], v[182:185]
	v_mfma_f32_16x16x32_bf16 v[178:181], v[28:31], v[178:181], v[186:189]
	s_nop 2
	ds_read_b128 v[186:189], v145 offset:128
	ds_read_b128 v[198:201], v145 offset:192
	s_waitcnt lgkmcnt(1)
	v_mfma_f32_16x16x32_bf16 v[202:205], v[24:27], v[186:189], v[36:39]
	v_mfma_f32_16x16x32_bf16 v[186:189], v[28:31], v[186:189], v[40:43]
	v_mfma_f32_16x16x32_bf16 v[48:51], v[20:23], v[190:193], v[48:51]
	v_mfma_f32_16x16x32_bf16 v[44:47], v[16:19], v[190:193], v[44:47]
	v_mfma_f32_16x16x32_bf16 v[40:43], v[20:23], v[174:177], v[170:173]
	v_mfma_f32_16x16x32_bf16 v[36:39], v[16:19], v[174:177], v[162:165]
	v_mfma_f32_16x16x32_bf16 v[28:31], v[20:23], v[194:197], v[182:185]
	v_mfma_f32_16x16x32_bf16 v[24:27], v[16:19], v[194:197], v[178:181]
	s_waitcnt lgkmcnt(0)
	v_mfma_f32_16x16x32_bf16 v[20:23], v[20:23], v[198:201], v[202:205]
	v_mfma_f32_16x16x32_bf16 v[16:19], v[16:19], v[198:201], v[186:189]
	s_and_saveexec_b64 s[0:1], vcc
	s_xor_b64 s[66:67], exec, s[0:1]
	s_cbranch_execz .LBB0_1731
	v_add_f32_e32 v32, 1.0, v69
	v_cmp_gt_f32_e32 vcc, s83, v32
	s_nop 1
	v_cndmask_b32_e64 v69, 0, 32, vcc
	v_ldexp_f32 v32, v32, v69
	v_log_f32_e32 v32, v32
	s_nop 0
	v_mul_f32_e32 v69, 0x3f317217, v32
	v_fma_f32 v69, v32, s84, -v69
	v_fmac_f32_e32 v69, 0x3377d1cf, v32
	v_fmac_f32_e32 v69, 0x3f317217, v32
	v_cmp_lt_f32_e64 s[10:11], |v32|, s85
	s_nop 1
	v_cndmask_b32_e64 v32, v32, v69, s[10:11]
	v_cndmask_b32_e32 v69, 0, v147, vcc
	v_sub_f32_e32 v32, v32, v69

; #define LBAR() do { asm volatile("s_waitcnt lgkmcnt(0)" ::: "memory"); __builtin_amdgcn_s_barrier(); asm volatile("" ::: "memory"); } while (0)
; template <bool UNUSED_>
; __device__ __forceinline__ void lru_phase(KA A, LAS unsigned char* lds, int tid, int lane, int wave) {
;     ...
;             float Ac = 1.f, hl = 0.f;
; #pragma unroll
;             for (int i = 0; i < 16; ++i) { const int t = 16 * tq + i; const float a = Af[t * LP + c]; hl = a * hl + Uf[t * LP + c]; Ac *= a; }
;             SEG[(tq * 128 + c) * 2] = Ac; SEG[(tq * 128 + c) * 2 + 1] = hl;
;         }
;         LBAR();
;         if (!FIN) {
.LBB0_1841:
	s_waitcnt lgkmcnt(0)
	s_barrier
	ds_read_b32 v9, v107 offset:50432
	ds_read_b32 v11, v108
	ds_read_b32 v12, v109 offset:50432
	ds_read_b32 v13, v110
	ds_read_b32 v8, v111 offset:50432
	ds_read_b32 v15, v112
	ds_read_b32 v10, v113 offset:50432
	ds_read_b32 v17, v114
	s_waitcnt lgkmcnt(6)
	v_fmac_f32_e32 v11, 0, v9
	s_waitcnt lgkmcnt(4)
	v_fmac_f32_e32 v13, v11, v12
	v_mul_f32_e32 v12, v9, v12
	s_waitcnt lgkmcnt(2)
	v_fmac_f32_e32 v15, v13, v8
	ds_read_b32 v14, v115 offset:50432
	ds_read_b32 v9, v116
	ds_read_b32 v16, v117 offset:50432
	ds_read_b32 v11, v118
	ds_read_b32 v18, v119 offset:50432
	ds_read_b32 v13, v120
	ds_read_b32 v20, v121 offset:50432
	ds_read_b32 v23, v122
	s_waitcnt lgkmcnt(8)
	v_fmac_f32_e32 v17, v15, v10
	s_waitcnt lgkmcnt(6)
	v_fmac_f32_e32 v9, v17, v14
	s_waitcnt lgkmcnt(4)
	v_fmac_f32_e32 v11, v9, v16
	s_waitcnt lgkmcnt(2)
	v_fmac_f32_e32 v13, v11, v18
	s_waitcnt lgkmcnt(0)
	v_fmac_f32_e32 v23, v13, v20
	ds_read_b32 v22, v123 offset:50432
	ds_read_b32 v13, v124
	ds_read_b32 v9, v125 offset:50432
	ds_read_b32 v11, v126
	ds_read_b32 v15, v127 offset:50432
	ds_read_b32 v17, v128
	ds_read_b32 v19, v129 offset:50432
	ds_read_b32 v21, v130
	s_waitcnt lgkmcnt(6)
	v_fmac_f32_e32 v13, v23, v22
	v_mul_f32_e32 v23, v12, v8
	v_mul_f32_e32 v24, v23, v10
	s_waitcnt lgkmcnt(4)
	v_pk_fma_f32 v[10:11], v[12:13], v[8:9], v[10:11]
	v_mov_b32_e32 v8, v9
	v_mov_b32_e32 v25, v11
	s_waitcnt lgkmcnt(3)
	v_pk_mul_f32 v[10:11], v[24:25], v[14:15]
	s_waitcnt lgkmcnt(2)
	v_pk_fma_f32 v[12:13], v[24:25], v[14:15], v[16:17]
	v_pk_mul_f32 v[10:11], v[10:11], v[16:17]
	ds_read_b32 v23, v131 offset:50432
	ds_read_b32 v17, v132
	ds_read_b32 v25, v133 offset:50432
	ds_read_b32 v27, v134
	ds_read_b32 v29, v135 offset:50432
	ds_read_b32 v31, v136
	ds_read_b32 v33, v137 offset:50432
	ds_read_b32 v35, v138
	v_mov_b32_e32 v12, v10
	s_waitcnt lgkmcnt(9)
	v_pk_mul_f32 v[10:11], v[10:11], v[18:19]
	s_waitcnt lgkmcnt(8)
	v_pk_fma_f32 v[12:13], v[12:13], v[18:19], v[20:21]
	v_pk_mul_f32 v[10:11], v[10:11], v[20:21]
	v_mov_b32_e32 v16, v9
	v_mov_b32_e32 v11, v13
	s_waitcnt lgkmcnt(7)
	v_pk_mul_f32 v[12:13], v[10:11], v[22:23]
	s_waitcnt lgkmcnt(6)
	v_pk_fma_f32 v[10:11], v[10:11], v[22:23], v[16:17]
	v_pk_mul_f32 v[8:9], v[12:13], v[8:9]
	v_mov_b32_e32 v12, v15
	v_mov_b32_e32 v10, v8
	v_mov_b32_e32 v24, v15
	v_pk_mul_f32 v[8:9], v[8:9], v[12:13]
	v_mov_b32_e32 v12, v19
	v_mov_b32_e32 v26, v19
	v_pk_mul_f32 v[8:9], v[8:9], v[12:13]
	s_waitcnt lgkmcnt(4)
	v_pk_fma_f32 v[10:11], v[10:11], v[24:25], v[26:27]
	v_mov_b32_e32 v28, v23
	v_mov_b32_e32 v9, v11
	s_waitcnt lgkmcnt(3)
	v_pk_mul_f32 v[10:11], v[8:9], v[28:29]
	v_mov_b32_e32 v12, v25
	v_mov_b32_e32 v30, v25
	v_pk_mul_f32 v[10:11], v[10:11], v[12:13]
	s_waitcnt lgkmcnt(2)
	v_pk_fma_f32 v[8:9], v[8:9], v[28:29], v[30:31]
	v_mov_b32_e32 v12, v29
	v_mov_b32_e32 v8, v10
	v_mov_b32_e32 v32, v29
	v_pk_mul_f32 v[10:11], v[10:11], v[12:13]
	s_waitcnt lgkmcnt(1)
	v_mov_b32_e32 v12, v33
	v_mov_b32_e32 v34, v33
	v_pk_mul_f32 v[10:11], v[10:11], v[12:13]
	s_waitcnt lgkmcnt(0)
	v_pk_fma_f32 v[8:9], v[8:9], v[32:33], v[34:35]
	s_mov_b64 s[10:11], -1
	v_mov_b32_e32 v11, v9
	ds_write_b64 v80, v[10:11]
	s_waitcnt lgkmcnt(0)
	s_waitcnt vmcnt(0)
	v_cndmask_b32_e64 v159, v159, 0, s[98:99]
	v_cndmask_b32_e64 v160, v158, 0, s[98:99]
	v_cndmask_b32_e64 v158, v210, 0, s[98:99]
	s_barrier
	s_and_b64 vcc, exec, s[62:63]
	s_cbranch_vccz .LBB0_1851
	s_load_dwordx2 s[10:11], s[28:29], 0x30
	s_lshl_b64 s[62:63], s[36:37], 12
	s_waitcnt lgkmcnt(0)
	s_add_u32 s10, s10, s62
	s_addc_u32 s11, s11, s63
	global_load_dword v8, v68, s[10:11]
	s_andn2_b64 vcc, exec, s[42:43]
	s_cbranch_vccnz .LBB0_1856
	ds_read_b64 v[10:11], v81
	s_waitcnt vmcnt(0) lgkmcnt(0)
	v_fmac_f32_e32 v11, v8, v10
	v_mov_b32_e32 v8, v11
	s_andn2_b64 vcc, exec, s[44:45]
	s_cbranch_vccz .LBB0_1857

; __global__ void __launch_bounds__(NTHREADS, 2) mega_fwd(Args Araw) {
	.amdhsa_kernel _Z8mega_fwd4Args
		.amdhsa_group_segment_fixed_size 0
		.amdhsa_private_segment_fixed_size 0
		.amdhsa_kernarg_size 520
		.amdhsa_user_sgpr_count 2
		.amdhsa_user_sgpr_dispatch_ptr 0
		.amdhsa_user_sgpr_queue_ptr 0
		.amdhsa_user_sgpr_kernarg_segment_ptr 1
		.amdhsa_user_sgpr_dispatch_id 0
		.amdhsa_user_sgpr_kernarg_preload_length 0
		.amdhsa_user_sgpr_kernarg_preload_offset 0
		.amdhsa_user_sgpr_private_segment_size 0
		.amdhsa_uses_dynamic_stack 0
		.amdhsa_enable_private_segment 0
		.amdhsa_system_sgpr_workgroup_id_x 1
		.amdhsa_system_sgpr_workgroup_id_y 0
		.amdhsa_system_sgpr_workgroup_id_z 0
		.amdhsa_system_sgpr_workgroup_info 0
		.amdhsa_system_vgpr_workitem_id 2
		.amdhsa_next_free_vgpr 237
		.amdhsa_next_free_sgpr 100
		.amdhsa_accum_offset 240
		.amdhsa_reserve_vcc 1
		.amdhsa_float_round_mode_32 0
		.amdhsa_float_round_mode_16_64 0
		.amdhsa_float_denorm_mode_32 3
		.amdhsa_float_denorm_mode_16_64 3
		.amdhsa_dx10_clamp 1
		.amdhsa_ieee_mode 1
		.amdhsa_fp16_overflow 0
		.amdhsa_tg_split 0
		.amdhsa_exception_fp_ieee_invalid_op 0
		.amdhsa_exception_fp_denorm_src 0
		.amdhsa_exception_fp_ieee_div_zero 0
		.amdhsa_exception_fp_ieee_overflow 0
		.amdhsa_exception_fp_ieee_underflow 0
		.amdhsa_exception_fp_ieee_inexact 0
		.amdhsa_exception_int_div_zero 0
	.end_amdhsa_kernel

; __global__ void __launch_bounds__(NTHREADS, 2) mega_fwd(Args Araw) {
amdhsa.kernels:
  - .agpr_count:     0
    .args:
      - .offset:         0
        .size:           264
        .value_kind:     by_value
      - .offset:         264
        .size:           4
        .value_kind:     hidden_block_count_x
      - .offset:         268
        .size:           4
        .value_kind:     hidden_block_count_y
      - .offset:         272
        .size:           4
        .value_kind:     hidden_block_count_z
      - .offset:         276
        .size:           2
        .value_kind:     hidden_group_size_x
      - .offset:         278
        .size:           2
        .value_kind:     hidden_group_size_y
      - .offset:         280
        .size:           2
        .value_kind:     hidden_group_size_z
      - .offset:         282
        .size:           2
        .value_kind:     hidden_remainder_x
      - .offset:         284
        .size:           2
        .value_kind:     hidden_remainder_y
      - .offset:         286
        .size:           2
        .value_kind:     hidden_remainder_z
      - .offset:         304
        .size:           8
        .value_kind:     hidden_global_offset_x
      - .offset:         312
        .size:           8
        .value_kind:     hidden_global_offset_y
      - .offset:         320
        .size:           8
        .value_kind:     hidden_global_offset_z
      - .offset:         328
        .size:           2
        .value_kind:     hidden_grid_dims
      - .offset:         352
        .size:           8
        .value_kind:     hidden_multigrid_sync_arg
      - .offset:         384
        .size:           4
        .value_kind:     hidden_dynamic_lds_size
    .group_segment_fixed_size: 0
    .kernarg_segment_align: 8
    .kernarg_segment_size: 520
    .language:       OpenCL C
    .language_version:
      - 2
      - 0
    .max_flat_workgroup_size: 512
    .name:           _Z8mega_fwd4Args
    .private_segment_fixed_size: 0
    .sgpr_count:     106
    .sgpr_spill_count: 27
    .symbol:         _Z8mega_fwd4Args.kd
    .uniform_work_group_size: 1
    .uses_dynamic_stack: false
    .vgpr_count:     237
    .vgpr_spill_count: 0
    .wavefront_size: 64
